# attn3 + s_sleep 6 per tile (all waves) + GDN post-barrier LDS read batching + DPP row reductions
# baseline (speedup 1.0000x reference)
; #define LAS __attribute__((address_space(3)))
; #define A_LOAD(t) do { kreg0 = *(const u32x4*)(kg + (size_t)((t) * 64 + kv0) * 768 + kc0 * 8); if (tid < 256) kreg1 = *(const u32x4*)(kg + (size_t)((t) * 64 + kv1) * 768 + kc1 * 8); \
;         vreg = *(const u32x4*)(vg + (size_t)(t) * 64 * 512); } while (0)
; __device__ __forceinline__ void attn_unit(LAS unsigned char* lds, const bf16* Q, const bf16* Kp, const bf16* V, bf16* Y, int b, int h, int qb) {
;     ...
;     for (int t = 0; t < NT; ++t) {
;         const int buf = t & 1;
;         if (t + 1 < NT) A_LOAD(t + 1);
;         const int jb = t - (NT - 4);
;         const bool skip = (jb >= 0) && (64 * jb > wid * 32 + 31);
;         if (!skip) {
;             f32x16 p0, p1;
;             const float nm = -m_run;
; #pragma unroll
;             for (int i = 0; i < 16; ++i) { p0[i] = nm; p1[i] = nm; }
;             LAS const unsigned char* kb = lds + KOFF + buf * KBUF + r32 * KPB + hi * 16;
;             LAS const unsigned char* vb = lds + VOFF + buf * VBUF + r32 * VPB + hi * 8;
; #pragma unroll
;             for (int d0 = 0; d0 < 6; ++d0) p0 = __builtin_amdgcn_mfma_f32_32x32x16_bf16(*(LAS const bf16x8*)(kb + 32 * d0), qr[d0], p0, 0, 0, 0);
; #pragma unroll
;             for (int d0 = 0; d0 < 6; ++d0) p1 = __builtin_amdgcn_mfma_f32_32x32x16_bf16(*(LAS const bf16x8*)(kb + 32 * KPB + 32 * d0), qr[d0], p1, 0, 0, 0);
.Lat_noload:
	s_add_i32 s10, s13, -1
	s_and_b32 s24, s10, 1
	s_add_i32 s10, s22, s13
	s_addk_i32 s10, 0xff83
	s_cmp_gt_i32 s10, -1
	s_cselect_b64 s[10:11], -1, 0
	s_add_i32 s25, s15, s23
	s_addk_i32 s25, 0xe100
	s_cmp_gt_i32 s25, s14
	s_cselect_b64 s[26:27], -1, 0
	s_and_b64 s[26:27], s[10:11], s[26:27]
	s_and_b64 vcc, exec, s[26:27]
	s_cbranch_vccnz .Lat_stage
	s_sleep 6
	s_mul_i32 s25, s24, 0x3400
	v_add_u32_e32 v110, s25, v117
	s_mul_i32 s25, s24, 0x2200
	v_add_u32_e32 v125, s25, v118
	ds_read_b128 v[172:175], v110
	ds_read_b128 v[176:179], v110 offset:32
	ds_read_b128 v[180:183], v110 offset:64
	ds_read_b128 v[184:187], v110 offset:96
	ds_read_b128 v[188:191], v110 offset:128
	ds_read_b128 v[192:195], v110 offset:160
	ds_read_b128 v[198:201], v110 offset:6656
	ds_read_b128 v[202:205], v110 offset:6688
	ds_read_b128 v[206:209], v110 offset:6720
	ds_read_b128 v[222:225], v110 offset:6752
	ds_read_b128 v[226:229], v110 offset:6784
	ds_read_b128 v[230:233], v110 offset:6816
	v_add_u32_e32 v124, 0x6800, v125
	v_add_u32_e32 v125, 0x7800, v125
	s_waitcnt lgkmcnt(11)
	v_mfma_f32_32x32x16_bf16 v[32:47], v[172:175], v[68:71], v[142:157]
	ds_read2_b64 v[234:237], v124 offset1:2
	s_waitcnt lgkmcnt(11)
	v_mfma_f32_32x32x16_bf16 v[32:47], v[176:179], v[72:75], v[32:47]
	ds_read2_b64 v[238:241], v124 offset0:4 offset1:6
	s_waitcnt lgkmcnt(11)
	v_mfma_f32_32x32x16_bf16 v[32:47], v[180:183], v[76:79], v[32:47]
	ds_read2_b64 v[242:245], v125 offset0:32 offset1:34
	s_waitcnt lgkmcnt(11)
	v_mfma_f32_32x32x16_bf16 v[32:47], v[184:187], v[80:83], v[32:47]
	ds_read2_b64 v[246:249], v125 offset0:36 offset1:38
	s_waitcnt lgkmcnt(11)
	v_mfma_f32_32x32x16_bf16 v[32:47], v[188:191], v[84:87], v[32:47]
	s_waitcnt lgkmcnt(10)
	v_mfma_f32_32x32x16_bf16 v[32:47], v[192:195], v[88:91], v[32:47]
	s_waitcnt lgkmcnt(9)
	v_mfma_f32_32x32x16_bf16 v[48:63], v[198:201], v[68:71], v[142:157]
	s_waitcnt lgkmcnt(8)
	v_mfma_f32_32x32x16_bf16 v[48:63], v[202:205], v[72:75], v[48:63]
	s_waitcnt lgkmcnt(7)
	v_mfma_f32_32x32x16_bf16 v[48:63], v[206:209], v[76:79], v[48:63]
	s_nop 5
	s_andn2_b64 vcc, exec, s[10:11]
	s_cbranch_vccnz .Lat_nomask0
	v_add_u32_e32 v126, s23, v119
	v_sub_u32_e32 v126, v116, v126
	v_add_u32_e32 v126, 0x1f00, v126
	v_cmp_gt_i32_e32 vcc, 0, v126
	v_cmp_gt_i32_e64 s[40:41], 1, v126
	v_cmp_gt_i32_e64 s[42:43], 2, v126
	v_cndmask_b32_e32 v32, v32, v221, vcc
	v_cmp_gt_i32_e32 vcc, 3, v126
	v_cndmask_b32_e64 v33, v33, v221, s[40:41]
	v_cmp_gt_i32_e64 s[40:41], 8, v126
	v_cndmask_b32_e64 v34, v34, v221, s[42:43]
	v_cmp_gt_i32_e64 s[42:43], 9, v126
	v_cndmask_b32_e32 v35, v35, v221, vcc
	v_cmp_gt_i32_e32 vcc, 10, v126
	v_cndmask_b32_e64 v36, v36, v221, s[40:41]
	v_cmp_gt_i32_e64 s[40:41], 11, v126
	v_cndmask_b32_e64 v37, v37, v221, s[42:43]
	v_cmp_gt_i32_e64 s[42:43], 16, v126
	v_cndmask_b32_e32 v38, v38, v221, vcc
	v_cmp_gt_i32_e32 vcc, 17, v126
	v_cndmask_b32_e64 v39, v39, v221, s[40:41]
	v_cmp_gt_i32_e64 s[40:41], 18, v126
	v_cndmask_b32_e64 v40, v40, v221, s[42:43]
	v_cmp_gt_i32_e64 s[42:43], 19, v126
	v_cndmask_b32_e32 v41, v41, v221, vcc
	v_cmp_gt_i32_e32 vcc, 24, v126
	v_cndmask_b32_e64 v42, v42, v221, s[40:41]
	v_cmp_gt_i32_e64 s[40:41], 25, v126
	v_cndmask_b32_e64 v43, v43, v221, s[42:43]
	v_cmp_gt_i32_e64 s[42:43], 26, v126
	v_cndmask_b32_e32 v44, v44, v221, vcc
	v_cmp_gt_i32_e32 vcc, 27, v126
	v_cndmask_b32_e64 v45, v45, v221, s[40:41]
	v_cndmask_b32_e64 v46, v46, v221, s[42:43]
	s_nop 0
	v_cndmask_b32_e32 v47, v47, v221, vcc

.LBB0_3679:
	v_add_u32_e32 v135, v120, v119
	v_add_u32_e32 v65, v120, v121
	ds_read_b128 v[44:47], v129 offset:18432
	ds_read_b128 v[60:63], v129
	ds_read_b128 v[66:69], v135 offset:27648
	ds_read_b128 v[70:73], v135 offset:9216
	ds_read_b128 v[144:147], v65 offset:27648
	ds_read_b128 v[148:151], v65 offset:9216
	s_waitcnt lgkmcnt(0)
	v_mfma_f32_16x16x32_bf16 v[140:143], v[44:47], v[66:69], 0
	s_add_i32 s10, 0, 0x18800
	v_mov_b32_e32 v80, s79
	v_add_u32_e32 v139, v116, v121
	v_mfma_f32_16x16x32_bf16 v[66:69], v[60:63], v[66:69], 0
	s_cmp_eq_u32 s80, -1
	s_waitcnt lgkmcnt(2)
	v_mfma_f32_16x16x32_bf16 v[70:73], v[60:63], v[70:73], 0
	s_waitcnt lgkmcnt(1)
	v_mfma_f32_16x16x32_bf16 v[152:155], v[44:47], v[144:147], 0
	v_mfma_f32_16x16x32_bf16 v[144:147], v[60:63], v[144:147], 0
	s_waitcnt lgkmcnt(0)
	v_mfma_f32_16x16x32_bf16 v[148:151], v[60:63], v[148:151], 0
	ds_read_b128 v[60:63], v129 offset:18496
	ds_read_b128 v[172:175], v129 offset:64
	ds_read_b128 v[44:47], v135 offset:27712
	ds_read_b128 v[176:179], v135 offset:9280
	s_waitcnt lgkmcnt(0)
	v_mfma_f32_16x16x32_bf16 v[180:183], v[60:63], v[44:47], v[140:143]
	s_nop 2
	v_add_u32_e32 v141, v116, v119
	v_mfma_f32_16x16x32_bf16 v[44:47], v[172:175], v[44:47], v[66:69]
	s_nop 2
	v_add_f32_e64 v106, v106, -v180
	v_add_f32_e64 v107, v107, -v181
	v_pk_add_f32 v[104:105], v[104:105], v[182:183] neg_lo:[0,1] neg_hi:[0,1]
	v_add_u32_e32 v142, s10, v123
	s_waitcnt lgkmcnt(0)
	v_mfma_f32_16x16x32_bf16 v[176:179], v[172:175], v[176:179], v[70:73]
	ds_read_b128 v[66:69], v65 offset:27712
	s_nop 1
	ds_read_b128 v[70:73], v65 offset:9280
	ds_read_b32 v143, v80
	v_add_u32_e32 v140, s10, v126
	s_waitcnt lgkmcnt(0)
	v_mfma_f32_16x16x32_bf16 v[70:73], v[172:175], v[70:73], v[148:151]
	s_nop 2
	v_add_u32_e32 v149, s10, v122
	v_mfma_f32_16x16x32_bf16 v[152:155], v[60:63], v[66:69], v[152:155]
	v_mfma_f32_16x16x32_bf16 v[60:63], v[172:175], v[66:69], v[144:147]
	ds_read_b128 v[66:69], v149
	s_nop 5
	v_pk_add_f32 v[100:101], v[100:101], v[152:153] neg_lo:[0,1] neg_hi:[0,1]
	v_pk_add_f32 v[102:103], v[102:103], v[154:155] neg_lo:[0,1] neg_hi:[0,1]
	s_waitcnt lgkmcnt(0)
	v_sub_f32_e32 v80, v143, v66
	v_mul_f32_e32 v80, 0x3fb8aa3b, v80
	v_exp_f32_e32 v144, v80
	v_sub_f32_e32 v80, v143, v67
	v_mul_f32_e32 v80, 0x3fb8aa3b, v80
	v_exp_f32_e32 v145, v80
	v_sub_f32_e32 v80, v143, v68
	v_mul_f32_e32 v80, 0x3fb8aa3b, v80
	v_exp_f32_e32 v150, v80
	v_sub_f32_e32 v80, v143, v69
	v_mul_f32_e32 v80, 0x3fb8aa3b, v80
	v_exp_f32_e32 v151, v80
	v_pk_mul_f32 v[146:147], v[106:107], v[144:145]
	v_cvt_pk_bf16_f32 v106, v106, v107
	v_cvt_pk_bf16_f32 v107, v104, v105
	v_pk_mul_f32 v[156:157], v[104:105], v[150:151]
	v_cvt_pk_bf16_f32 v104, v146, v147
	v_cvt_pk_bf16_f32 v105, v156, v157
	ds_write2st64_b64 v141, v[106:107], v[104:105] offset0:72 offset1:90
	ds_read_b32 v80, v142
	v_pk_mul_f32 v[106:107], v[102:103], v[150:151]
	s_waitcnt lgkmcnt(0)
	v_sub_f32_e32 v104, v66, v80
	v_mul_f32_e32 v104, 0x3fb8aa3b, v104
	v_exp_f32_e32 v104, v104
	s_nop 0
	v_mul_f32_e32 v104, v176, v104
	v_cvt_pk_bf16_f32 v104, v104, s0
	v_cndmask_b32_e64 v104, v104, 0, s[40:41]
	ds_write_b16 v131, v104 offset:55296
	v_sub_f32_e32 v104, v67, v80
	v_mul_f32_e32 v104, 0x3fb8aa3b, v104
	v_exp_f32_e32 v104, v104
	s_nop 0
	v_mul_f32_e32 v104, v177, v104
	v_cvt_pk_bf16_f32 v104, v104, s0
	v_cndmask_b32_e64 v104, v104, 0, s[42:43]
	ds_write_b16 v131, v104 offset:55440
	v_sub_f32_e32 v104, v68, v80
	v_mul_f32_e32 v104, 0x3fb8aa3b, v104
	v_exp_f32_e32 v104, v104
	v_sub_f32_e32 v80, v69, v80
	v_mul_f32_e32 v80, 0x3fb8aa3b, v80
	v_exp_f32_e32 v80, v80
	v_mul_f32_e32 v104, v178, v104
	v_cvt_pk_bf16_f32 v104, v104, s0
	v_cndmask_b32_e64 v104, v104, 0, s[44:45]
	v_mul_f32_e32 v80, v179, v80
	ds_write_b16 v131, v104 offset:55584
	v_cvt_pk_bf16_f32 v80, v80, s0
	v_pk_mul_f32 v[104:105], v[100:101], v[144:145]
	v_cndmask_b32_e64 v80, v80, 0, s[46:47]
	v_cvt_pk_bf16_f32 v100, v100, v101
	v_cvt_pk_bf16_f32 v101, v102, v103
	v_cvt_pk_bf16_f32 v102, v104, v105
	v_cvt_pk_bf16_f32 v103, v106, v107
	ds_write_b16 v131, v80 offset:55728
	ds_write2st64_b64 v139, v[100:101], v[102:103] offset0:72 offset1:90
	ds_read_b32 v80, v140
	s_waitcnt lgkmcnt(0)
	v_sub_f32_e32 v100, v66, v80
	v_mul_f32_e32 v100, 0x3fb8aa3b, v100
	v_exp_f32_e32 v100, v100
	s_nop 0
	v_mul_f32_e32 v70, v70, v100
	v_cvt_pk_bf16_f32 v70, v70, s0
	v_cndmask_b32_e64 v70, v70, 0, s[48:49]
	ds_write_b16 v132, v70 offset:55296
	v_sub_f32_e32 v70, v67, v80
	v_mul_f32_e32 v70, 0x3fb8aa3b, v70
	v_exp_f32_e32 v70, v70
	s_nop 0
	v_mul_f32_e32 v70, v71, v70
	v_cvt_pk_bf16_f32 v70, v70, s0
	v_cndmask_b32_e64 v70, v70, 0, s[50:51]
	ds_write_b16 v132, v70 offset:55440
	v_sub_f32_e32 v70, v68, v80
	v_mul_f32_e32 v70, 0x3fb8aa3b, v70
	v_exp_f32_e32 v70, v70
	s_nop 0
	v_mul_f32_e32 v70, v72, v70
	v_cvt_pk_bf16_f32 v70, v70, s0
	v_cndmask_b32_e64 v70, v70, 0, s[52:53]
	ds_write_b16 v132, v70 offset:55584
	v_sub_f32_e32 v70, v69, v80
	v_mul_f32_e32 v70, 0x3fb8aa3b, v70
	v_exp_f32_e32 v70, v70
	s_nop 0
	v_mul_f32_e32 v70, v73, v70
	v_cvt_pk_bf16_f32 v70, v70, s0
	v_cndmask_b32_e64 v70, v70, 0, s[54:55]
	ds_write_b16 v132, v70 offset:55728
	s_cbranch_scc1 .LBB0_3681
	ds_read_b128 v[100:103], v130
	ds_read_b128 v[70:73], v130 offset:16
	s_lshl_b64 s[10:11], s[80:81], 17
	s_waitcnt lgkmcnt(0)
	v_pk_mul_f32 v[104:105], v[102:103], v[102:103]
	v_pk_mul_f32 v[106:107], v[100:101], v[100:101]
	s_nop 0
	v_pk_mov_b32 v[144:145], v[106:107], v[104:105] op_sel:[1,0]
	v_mov_b32_e32 v107, v105
	v_pk_add_f32 v[104:105], v[144:145], v[106:107]
	s_waitcnt lgkmcnt(0)
	v_pk_mul_f32 v[106:107], v[72:73], v[72:73]
	v_pk_mul_f32 v[144:145], v[70:71], v[70:71]
	v_mov_b32_e32 v146, v106
	v_mov_b32_e32 v147, v144
	v_mov_b32_e32 v144, v107
	v_pk_add_f32 v[106:107], v[146:147], v[144:145]
	v_add_f32_e32 v80, v104, v105
	v_add_f32_e32 v80, v80, v107
	v_add_f32_e32 v80, v106, v80
	v_and_b32_e32 v105, 0xffff0000, v56
	s_nop 0
	v_add_f32_dpp v80, v80, v80 quad_perm:[1,0,3,2] row_mask:0xf bank_mask:0xf
	s_nop 1
	v_add_f32_dpp v80, v80, v80 quad_perm:[2,3,0,1] row_mask:0xf bank_mask:0xf
	s_nop 1
	v_add_f32_dpp v80, v80, v80 row_half_mirror row_mask:0xf bank_mask:0xf
	v_fmamk_f32 v80, v80, 0x3c800000, v162
	v_cmp_gt_f32_e32 vcc, s57, v80
	v_mul_f32_e32 v104, 0x4b800000, v80
	s_nop 0
	v_cndmask_b32_e32 v80, v80, v104, vcc
	v_rsq_f32_e32 v80, v80
	s_nop 0
	v_mul_f32_e32 v104, 0x45800000, v80
	v_cndmask_b32_e32 v80, v80, v104, vcc
	v_lshlrev_b32_e32 v104, 16, v56
	v_mul_f32_e32 v56, 0xbfb8aa3b, v104
	v_exp_f32_e32 v56, v56
	v_pk_mul_f32 v[100:101], v[100:101], v[80:81] op_sel_hi:[1,0]
	v_pk_mul_f32 v[102:103], v[102:103], v[80:81] op_sel_hi:[1,0]
	v_pk_mul_f32 v[100:101], v[12:13], v[100:101]
	v_add_f32_e32 v56, 1.0, v56
	v_rcp_f32_e32 v106, v56
	v_mul_f32_e32 v56, 0xbfb8aa3b, v105
	v_exp_f32_e32 v56, v56
	v_pk_mul_f32 v[102:103], v[14:15], v[102:103]
	v_pk_mul_f32 v[70:71], v[70:71], v[80:81] op_sel_hi:[1,0]
	v_pk_mul_f32 v[72:73], v[72:73], v[80:81] op_sel_hi:[1,0]
	v_add_f32_e32 v56, 1.0, v56
	v_rcp_f32_e32 v107, v56
	v_lshlrev_b32_e32 v56, 16, v57
	v_and_b32_e32 v57, 0xffff0000, v57
	v_pk_mul_f32 v[70:71], v[0:1], v[70:71]
	v_pk_mul_f32 v[104:105], v[106:107], v[104:105]
	v_pk_mul_f32 v[72:73], v[2:3], v[72:73]
	v_pk_mul_f32 v[100:101], v[104:105], v[100:101]
	v_mul_f32_e32 v104, 0xbfb8aa3b, v56
	v_mul_f32_e32 v105, 0xbfb8aa3b, v57
	v_exp_f32_e32 v104, v104
	v_exp_f32_e32 v105, v105
	v_add_f32_e32 v104, 1.0, v104
	v_add_f32_e32 v105, 1.0, v105
	v_rcp_f32_e32 v104, v104
	v_rcp_f32_e32 v105, v105
	s_nop 0
	v_pk_mul_f32 v[56:57], v[104:105], v[56:57]
	s_nop 0
	v_pk_mul_f32 v[102:103], v[56:57], v[102:103]
	v_lshlrev_b32_e32 v56, 16, v58
	v_and_b32_e32 v57, 0xffff0000, v58
	v_mul_f32_e32 v58, 0xbfb8aa3b, v56
	v_exp_f32_e32 v58, v58
	s_nop 0
	v_add_f32_e32 v58, 1.0, v58
	v_rcp_f32_e32 v104, v58
	v_mul_f32_e32 v58, 0xbfb8aa3b, v57
	v_exp_f32_e32 v58, v58
	s_nop 0
	v_add_f32_e32 v58, 1.0, v58
	v_rcp_f32_e32 v105, v58
	s_nop 0
	v_pk_mul_f32 v[56:57], v[104:105], v[56:57]
	s_nop 0
	v_pk_mul_f32 v[70:71], v[56:57], v[70:71]
	v_lshlrev_b32_e32 v56, 16, v59
	v_and_b32_e32 v57, 0xffff0000, v59
	v_mul_f32_e32 v58, 0xbfb8aa3b, v56
	v_mul_f32_e32 v59, 0xbfb8aa3b, v57
	v_exp_f32_e32 v58, v58
	v_exp_f32_e32 v59, v59
	v_add_f32_e32 v58, 1.0, v58
	v_add_f32_e32 v59, 1.0, v59
	v_rcp_f32_e32 v58, v58
	v_rcp_f32_e32 v59, v59
	s_nop 0
	v_pk_mul_f32 v[56:57], v[58:59], v[56:57]
	s_nop 0
	v_pk_mul_f32 v[72:73], v[56:57], v[72:73]
	v_cvt_pk_bf16_f32 v56, v100, v101
	v_cvt_pk_bf16_f32 v57, v102, v103
	v_cvt_pk_bf16_f32 v58, v70, v71
	v_cvt_pk_bf16_f32 v59, v72, v73
	v_lshl_add_u64 v[70:71], v[86:87], 0, s[10:11]
	global_store_dwordx4 v[70:71], v[56:59], off offset:1024
.LBB0_3681:
	s_nop 1
	v_mul_f32_e32 v57, 0x3fb8aa3b, v66
	v_exp_f32_e32 v104, v57
	v_mul_f32_e32 v57, 0x3fb8aa3b, v67
	v_exp_f32_e32 v105, v57
	v_mul_f32_e32 v57, 0x3fb8aa3b, v68
	v_mul_f32_e32 v56, 0x3fb8aa3b, v143
	v_exp_f32_e32 v106, v57
	v_mul_f32_e32 v57, 0x3fb8aa3b, v69
	v_exp_f32_e32 v107, v57
	v_exp_f32_e32 v80, v56
	s_waitcnt lgkmcnt(0)
	s_barrier
	ds_read_b128 v[56:59], v129 offset:55296
	ds_read_b128 v[70:73], v135 offset:36864
	ds_read_b128 v[66:69], v129 offset:64512
	ds_read_b128 v[100:103], v135 offset:46080
	ds_read_b128 v[216:219], v65 offset:36864
	ds_read_b128 v[222:225], v65 offset:46080
	ds_read_b128 v[226:229], v129 offset:55360
	ds_read_b128 v[234:237], v135 offset:36928
	ds_read_b128 v[242:245], v65 offset:36928
	ds_read_b128 v[230:233], v129 offset:64576
	ds_read_b128 v[238:241], v135 offset:46144
	ds_read_b128 v[246:249], v65 offset:46144
	v_pk_mul_f32 v[46:47], v[46:47], v[106:107]
	v_pk_mul_f32 v[44:45], v[44:45], v[104:105]
	v_pk_mul_f32 v[50:51], v[50:51], v[80:81] op_sel_hi:[1,0]
	v_pk_mul_f32 v[48:49], v[48:49], v[80:81] op_sel_hi:[1,0]
	s_waitcnt lgkmcnt(10)
	v_mfma_f32_16x16x32_bf16 v[44:47], v[56:59], v[70:73], v[44:47]
	v_mul_f32_e64 v62, v62, v106
	v_mul_f32_e64 v63, v63, v107
	v_pk_mul_f32 v[60:61], v[60:61], v[104:105]
	v_pk_mul_f32 v[54:55], v[54:55], v[80:81] op_sel_hi:[1,0]
	s_waitcnt lgkmcnt(8)
	v_mfma_f32_16x16x32_bf16 v[48:51], v[66:69], v[100:103], v[48:51]
	v_pk_mul_f32 v[52:53], v[52:53], v[80:81] op_sel_hi:[1,0]
	v_add_u32_e32 v147, v117, v119
	s_waitcnt lgkmcnt(7)
	v_mfma_f32_16x16x32_bf16 v[56:59], v[56:59], v[216:219], v[60:63]
	v_add_u32_e32 v148, v117, v121
	s_waitcnt lgkmcnt(6)
	v_mfma_f32_16x16x32_bf16 v[52:55], v[66:69], v[222:225], v[52:55]
	s_waitcnt lgkmcnt(4)
	v_mfma_f32_16x16x32_bf16 v[44:47], v[226:229], v[234:237], v[44:47]
	s_waitcnt lgkmcnt(3)
	v_mfma_f32_16x16x32_bf16 v[56:59], v[226:229], v[242:245], v[56:59]
	s_waitcnt lgkmcnt(1)
	v_mfma_f32_16x16x32_bf16 v[48:51], v[230:233], v[238:241], v[48:51]
	s_waitcnt lgkmcnt(0)
	v_mfma_f32_16x16x32_bf16 v[52:55], v[230:233], v[246:249], v[52:55]
	s_nop 1
	ds_write2_b32 v133, v44, v45 offset1:68
	ds_write2_b32 v133, v46, v47 offset0:136 offset1:204
	s_nop 5
	v_cvt_pk_bf16_f32 v44, v48, v49
	v_cvt_pk_bf16_f32 v45, v50, v51
	ds_write_b64 v147, v[44:45] offset:27648
	ds_write2_b32 v134, v56, v57 offset1:68
	ds_write2_b32 v134, v58, v59 offset0:136 offset1:204
	v_cvt_pk_bf16_f32 v44, v52, v53
	v_cvt_pk_bf16_f32 v45, v54, v55
	ds_write_b64 v148, v[44:45] offset:27648
	s_cmp_eq_u32 s101, 0
	s_cbranch_scc1 .Lg_noD1
	s_and_b64 vcc, exec, s[8:9]
	s_cbranch_vccz .Lg_w0
	s_waitcnt vmcnt(14)
	s_branch .Lg_w1

.LBB0_3688:
	v_and_b32_e32 v105, 0xffff0000, v81
	v_lshlrev_b32_e32 v104, 16, v81
	ds_read_b128 v[56:59], v129 offset:18432
	ds_read_b128 v[60:63], v129
	ds_read_b128 v[66:69], v135 offset:27648
	ds_read_b128 v[70:73], v135 offset:9216
	ds_read_b128 v[78:81], v65 offset:27648
	ds_read_b128 v[150:153], v65 offset:9216
	s_waitcnt lgkmcnt(0)
	v_mfma_f32_16x16x32_bf16 v[74:77], v[56:59], v[66:69], 0
	v_and_b32_e32 v103, 0xffff0000, v136
	v_lshlrev_b32_e32 v102, 16, v136
	v_mov_b32_e32 v136, s79
	v_mfma_f32_16x16x32_bf16 v[66:69], v[60:63], v[66:69], 0
	v_and_b32_e32 v107, 0xffff0000, v137
	v_lshlrev_b32_e32 v106, 16, v137
	v_and_b32_e32 v101, 0xffff0000, v138
	v_mfma_f32_16x16x32_bf16 v[70:73], v[60:63], v[70:73], 0
	v_lshlrev_b32_e32 v100, 16, v138
	v_mfma_f32_16x16x32_bf16 v[154:157], v[56:59], v[78:81], 0
	v_mfma_f32_16x16x32_bf16 v[172:175], v[60:63], v[78:81], 0
	v_mfma_f32_16x16x32_bf16 v[150:153], v[60:63], v[150:153], 0
	ds_read_b128 v[60:63], v129 offset:18496
	ds_read_b128 v[176:179], v129 offset:64
	ds_read_b128 v[56:59], v135 offset:27712
	ds_read_b128 v[78:81], v135 offset:9280
	s_waitcnt lgkmcnt(0)
	v_mfma_f32_16x16x32_bf16 v[180:183], v[60:63], v[56:59], v[74:77]
	v_mfma_f32_16x16x32_bf16 v[56:59], v[176:179], v[56:59], v[66:69]
	v_mfma_f32_16x16x32_bf16 v[78:81], v[176:179], v[78:81], v[70:73]
	s_nop 1
	ds_read_b128 v[66:69], v65 offset:27712
	ds_read_b128 v[70:73], v65 offset:9280
	ds_read_b32 v137, v136
	s_waitcnt lgkmcnt(0)
	v_mul_f32_e32 v136, 0x3fb8aa3b, v137
	v_mfma_f32_16x16x32_bf16 v[74:77], v[60:63], v[66:69], v[154:157]
	v_exp_f32_e32 v136, v136
	v_mfma_f32_16x16x32_bf16 v[60:63], v[176:179], v[66:69], v[172:175]
	v_mfma_f32_16x16x32_bf16 v[66:69], v[176:179], v[70:73], v[150:153]
	ds_read_b128 v[70:73], v149
	s_nop 0
	v_pk_add_f32 v[172:173], v[104:105], v[182:183] neg_lo:[0,1] neg_hi:[0,1]
	s_nop 1
	v_pk_add_f32 v[74:75], v[100:101], v[74:75] neg_lo:[0,1] neg_hi:[0,1]
	v_pk_add_f32 v[152:153], v[106:107], v[180:181] neg_lo:[0,1] neg_hi:[0,1]
	v_pk_add_f32 v[76:77], v[102:103], v[76:77] neg_lo:[0,1] neg_hi:[0,1]
	s_waitcnt lgkmcnt(0)
	v_sub_f32_e32 v138, v137, v70
	v_mul_f32_e32 v138, 0x3fb8aa3b, v138
	v_exp_f32_e32 v150, v138
	v_sub_f32_e32 v138, v137, v71
	v_mul_f32_e32 v138, 0x3fb8aa3b, v138
	v_exp_f32_e32 v151, v138
	v_sub_f32_e32 v138, v137, v72
	v_sub_f32_e32 v137, v137, v73
	v_mul_f32_e32 v138, 0x3fb8aa3b, v138
	v_mul_f32_e32 v137, 0x3fb8aa3b, v137
	v_exp_f32_e32 v156, v138
	v_exp_f32_e32 v157, v137
	v_pk_mul_f32 v[154:155], v[152:153], v[150:151]
	v_cvt_pk_bf16_f32 v152, v152, v153
	v_cvt_pk_bf16_f32 v153, v172, v173
	v_pk_mul_f32 v[174:175], v[172:173], v[156:157]
	v_cvt_pk_bf16_f32 v154, v154, v155
	v_cvt_pk_bf16_f32 v155, v174, v175
	ds_write2st64_b64 v141, v[152:153], v[154:155] offset0:72 offset1:90
	ds_read_b32 v137, v142
	v_pk_mul_f32 v[150:151], v[74:75], v[150:151]
	v_pk_mul_f32 v[152:153], v[76:77], v[156:157]
	v_cvt_pk_bf16_f32 v74, v74, v75
	v_cvt_pk_bf16_f32 v75, v76, v77
	s_waitcnt lgkmcnt(0)
	v_sub_f32_e32 v138, v70, v137
	v_mul_f32_e32 v138, 0x3fb8aa3b, v138
	v_exp_f32_e32 v138, v138
	v_cvt_pk_bf16_f32 v76, v150, v151
	v_cvt_pk_bf16_f32 v77, v152, v153
	v_mul_f32_e32 v78, v78, v138
	v_sub_f32_e32 v138, v71, v137
	v_mul_f32_e32 v138, 0x3fb8aa3b, v138
	v_exp_f32_e32 v138, v138
	v_cvt_pk_bf16_f32 v78, v78, s0
	v_cndmask_b32_e64 v78, v78, 0, s[40:41]
	ds_write_b16 v131, v78 offset:55296
	v_mul_f32_e32 v79, v79, v138
	v_sub_f32_e32 v138, v72, v137
	v_sub_f32_e32 v137, v73, v137
	v_mul_f32_e32 v138, 0x3fb8aa3b, v138
	v_mul_f32_e32 v137, 0x3fb8aa3b, v137
	v_exp_f32_e32 v138, v138
	v_exp_f32_e32 v137, v137
	v_cvt_pk_bf16_f32 v79, v79, s0
	v_cndmask_b32_e64 v79, v79, 0, s[42:43]
	v_mul_f32_e32 v80, v80, v138
	v_mul_f32_e32 v81, v81, v137
	v_cvt_pk_bf16_f32 v80, v80, s0
	v_cvt_pk_bf16_f32 v81, v81, s0
	v_cndmask_b32_e64 v80, v80, 0, s[44:45]
	v_cndmask_b32_e64 v81, v81, 0, s[46:47]
	ds_write_b16 v131, v79 offset:55440
	ds_write_b16 v131, v80 offset:55584
	ds_write_b16 v131, v81 offset:55728
	ds_write2st64_b64 v139, v[74:75], v[76:77] offset0:72 offset1:90
	ds_read_b32 v74, v140
	v_mul_f32_e32 v78, 0x3fb8aa3b, v70
	v_mul_f32_e32 v79, 0x3fb8aa3b, v71
	v_mul_f32_e32 v80, 0x3fb8aa3b, v72
	v_mul_f32_e32 v81, 0x3fb8aa3b, v73
	s_waitcnt lgkmcnt(0)
	v_sub_f32_e32 v70, v70, v74
	v_mul_f32_e32 v70, 0x3fb8aa3b, v70
	v_exp_f32_e32 v70, v70
	v_exp_f32_e32 v78, v78
	v_exp_f32_e32 v79, v79
	v_exp_f32_e32 v80, v80
	v_mul_f32_e32 v66, v66, v70
	v_cvt_pk_bf16_f32 v66, v66, s0
	v_cndmask_b32_e64 v66, v66, 0, s[48:49]
	ds_write_b16 v132, v66 offset:55296
	v_sub_f32_e32 v66, v71, v74
	v_mul_f32_e32 v66, 0x3fb8aa3b, v66
	v_exp_f32_e32 v66, v66
	v_exp_f32_e32 v81, v81
	v_pk_mul_f32 v[56:57], v[56:57], v[78:79]
	v_pk_mul_f32 v[50:51], v[50:51], v[136:137] op_sel_hi:[1,0]
	v_mul_f32_e32 v66, v67, v66
	v_cvt_pk_bf16_f32 v66, v66, s0
	v_cndmask_b32_e64 v66, v66, 0, s[50:51]
	ds_write_b16 v132, v66 offset:55440
	v_sub_f32_e32 v66, v72, v74
	v_mul_f32_e32 v66, 0x3fb8aa3b, v66
	v_exp_f32_e32 v66, v66
	v_pk_mul_f32 v[58:59], v[58:59], v[80:81]
	v_pk_mul_f32 v[48:49], v[48:49], v[136:137] op_sel_hi:[1,0]
	v_pk_mul_f32 v[62:63], v[62:63], v[80:81]
	v_mul_f32_e32 v66, v68, v66
	v_cvt_pk_bf16_f32 v66, v66, s0
	v_cndmask_b32_e64 v66, v66, 0, s[52:53]
	ds_write_b16 v132, v66 offset:55584
	v_sub_f32_e32 v66, v73, v74
	v_mul_f32_e32 v66, 0x3fb8aa3b, v66
	v_exp_f32_e32 v66, v66
	v_pk_mul_f32 v[60:61], v[60:61], v[78:79]
	v_pk_mul_f32 v[54:55], v[54:55], v[136:137] op_sel_hi:[1,0]
	v_pk_mul_f32 v[52:53], v[52:53], v[136:137] op_sel_hi:[1,0]
	v_mul_f32_e32 v66, v69, v66
	v_cvt_pk_bf16_f32 v66, v66, s0
	v_cndmask_b32_e64 v66, v66, 0, s[54:55]
	ds_write_b16 v132, v66 offset:55728
	ds_read_b128 v[70:73], v130
	ds_read_b128 v[66:69], v130 offset:16
	s_waitcnt lgkmcnt(0)
	v_pk_mul_f32 v[74:75], v[72:73], v[72:73]
	v_pk_mul_f32 v[76:77], v[70:71], v[70:71]
	s_nop 0
	v_pk_mov_b32 v[138:139], v[76:77], v[74:75] op_sel:[1,0]
	v_mov_b32_e32 v77, v75
	v_pk_add_f32 v[74:75], v[138:139], v[76:77]
	v_pk_mul_f32 v[76:77], v[68:69], v[68:69]
	v_pk_mul_f32 v[138:139], v[66:67], v[66:67]
	v_mov_b32_e32 v140, v76
	v_mov_b32_e32 v141, v138
	v_mov_b32_e32 v138, v77
	v_pk_add_f32 v[76:77], v[140:141], v[138:139]
	v_add_f32_e32 v74, v74, v75
	v_add_f32_e32 v74, v74, v77
	v_add_f32_e32 v74, v76, v74
	v_lshlrev_b32_e32 v76, 16, v40
	v_and_b32_e32 v77, 0xffff0000, v40
	v_add_f32_dpp v74, v74, v74 quad_perm:[1,0,3,2] row_mask:0xf bank_mask:0xf
	v_mul_f32_e32 v40, 0xbfb8aa3b, v76
	v_exp_f32_e32 v40, v40
	v_add_f32_dpp v74, v74, v74 quad_perm:[2,3,0,1] row_mask:0xf bank_mask:0xf
	v_add_f32_e32 v40, 1.0, v40
	v_rcp_f32_e32 v138, v40
	v_mul_f32_e32 v40, 0xbfb8aa3b, v77
	v_add_f32_dpp v74, v74, v74 row_half_mirror row_mask:0xf bank_mask:0xf
	v_exp_f32_e32 v40, v40
	s_nop 0
	v_fmamk_f32 v74, v74, 0x3c800000, v162
	v_cmp_gt_f32_e32 vcc, s57, v74
	v_mul_f32_e32 v75, 0x4b800000, v74
	v_add_f32_e32 v40, 1.0, v40
	v_cndmask_b32_e32 v74, v74, v75, vcc
	v_rsq_f32_e32 v74, v74
	v_rcp_f32_e32 v139, v40
	v_lshlrev_b32_e32 v40, 16, v41
	v_and_b32_e32 v41, 0xffff0000, v41
	v_mul_f32_e32 v75, 0x45800000, v74
	v_cndmask_b32_e32 v74, v74, v75, vcc
	v_pk_mul_f32 v[70:71], v[70:71], v[74:75] op_sel_hi:[1,0]
	v_mul_f32_e32 v75, 0xbfb8aa3b, v40
	v_exp_f32_e32 v75, v75
	v_pk_mul_f32 v[70:71], v[12:13], v[70:71]
	v_pk_mul_f32 v[76:77], v[138:139], v[76:77]
	s_andn2_b64 vcc, exec, s[8:9]
	v_add_f32_e32 v75, 1.0, v75
	v_pk_mul_f32 v[70:71], v[76:77], v[70:71]
	v_rcp_f32_e32 v76, v75
	v_pk_mul_f32 v[72:73], v[72:73], v[74:75] op_sel_hi:[1,0]
	v_mul_f32_e32 v75, 0xbfb8aa3b, v41
	v_exp_f32_e32 v75, v75
	v_pk_mul_f32 v[72:73], v[14:15], v[72:73]
	v_add_f32_e32 v75, 1.0, v75
	v_rcp_f32_e32 v77, v75
	v_pk_mul_f32 v[66:67], v[66:67], v[74:75] op_sel_hi:[1,0]
	v_pk_mul_f32 v[68:69], v[68:69], v[74:75] op_sel_hi:[1,0]
	v_pk_mul_f32 v[66:67], v[0:1], v[66:67]
	v_pk_mul_f32 v[40:41], v[76:77], v[40:41]
	v_pk_mul_f32 v[68:69], v[2:3], v[68:69]
	v_pk_mul_f32 v[72:73], v[40:41], v[72:73]
	v_lshlrev_b32_e32 v40, 16, v42
	v_and_b32_e32 v41, 0xffff0000, v42
	v_mul_f32_e32 v42, 0xbfb8aa3b, v40
	v_exp_f32_e32 v42, v42
	s_nop 0
	v_add_f32_e32 v42, 1.0, v42
	v_rcp_f32_e32 v76, v42
	v_mul_f32_e32 v42, 0xbfb8aa3b, v41
	v_exp_f32_e32 v42, v42
	s_nop 0
	v_add_f32_e32 v42, 1.0, v42
	v_rcp_f32_e32 v77, v42
	s_nop 0
	v_pk_mul_f32 v[40:41], v[76:77], v[40:41]
	s_nop 0
	v_pk_mul_f32 v[66:67], v[40:41], v[66:67]
	v_lshlrev_b32_e32 v40, 16, v43
	v_and_b32_e32 v41, 0xffff0000, v43
	v_mul_f32_e32 v42, 0xbfb8aa3b, v40
	v_mul_f32_e32 v43, 0xbfb8aa3b, v41
	v_exp_f32_e32 v42, v42
	v_exp_f32_e32 v43, v43
	v_add_f32_e32 v42, 1.0, v42
	v_add_f32_e32 v43, 1.0, v43
	v_rcp_f32_e32 v42, v42
	v_rcp_f32_e32 v43, v43
	s_nop 0
	v_pk_mul_f32 v[40:41], v[42:43], v[40:41]
	s_nop 0
	v_pk_mul_f32 v[68:69], v[40:41], v[68:69]
	v_cvt_pk_bf16_f32 v40, v70, v71
	v_cvt_pk_bf16_f32 v41, v72, v73
	v_cvt_pk_bf16_f32 v42, v66, v67
	v_cvt_pk_bf16_f32 v43, v68, v69
	v_lshl_add_u64 v[66:67], s[0:1], 0, v[98:99]
	global_store_dwordx4 v[66:67], v[40:43], off
	s_waitcnt lgkmcnt(0)
	s_barrier
	ds_read_b128 v[40:43], v129 offset:55296
	ds_read_b128 v[70:73], v135 offset:36864
	ds_read_b128 v[66:69], v83
	ds_read_b128 v[74:77], v135 offset:46080
	ds_read_b128 v[216:219], v65 offset:36864
	ds_read_b128 v[222:225], v65 offset:46080
	ds_read_b128 v[226:229], v129 offset:55360
	ds_read_b128 v[234:237], v135 offset:36928
	ds_read_b128 v[242:245], v65 offset:36928
	ds_read_b128 v[230:233], v83 offset:64
	ds_read_b128 v[238:241], v135 offset:46144
	ds_read_b128 v[246:249], v65 offset:46144
	s_waitcnt lgkmcnt(10)
	v_mfma_f32_16x16x32_bf16 v[56:59], v[40:43], v[70:73], v[56:59]
	s_waitcnt lgkmcnt(8)
	v_mfma_f32_16x16x32_bf16 v[48:51], v[66:69], v[74:77], v[48:51]
	s_waitcnt lgkmcnt(7)
	v_mfma_f32_16x16x32_bf16 v[40:43], v[40:43], v[216:219], v[60:63]
	s_waitcnt lgkmcnt(6)
	v_mfma_f32_16x16x32_bf16 v[52:55], v[66:69], v[222:225], v[52:55]
	s_waitcnt lgkmcnt(4)
	v_mfma_f32_16x16x32_bf16 v[56:59], v[226:229], v[234:237], v[56:59]
	s_waitcnt lgkmcnt(3)
	v_mfma_f32_16x16x32_bf16 v[40:43], v[226:229], v[242:245], v[40:43]
	s_waitcnt lgkmcnt(1)
	v_mfma_f32_16x16x32_bf16 v[48:51], v[230:233], v[238:241], v[48:51]
	s_waitcnt lgkmcnt(0)
	v_mfma_f32_16x16x32_bf16 v[52:55], v[230:233], v[246:249], v[52:55]
	s_nop 1
	ds_write2_b32 v133, v56, v57 offset1:68
	ds_write2_b32 v133, v58, v59 offset0:136 offset1:204
	s_nop 5
	v_cvt_pk_bf16_f32 v56, v48, v49
	v_cvt_pk_bf16_f32 v57, v50, v51
	ds_write_b64 v147, v[56:57] offset:27648
	ds_write2_b32 v134, v40, v41 offset1:68
	ds_write2_b32 v134, v42, v43 offset0:136 offset1:204
	v_cvt_pk_bf16_f32 v40, v52, v53
	v_cvt_pk_bf16_f32 v41, v54, v55
	ds_write_b64 v148, v[40:41] offset:27648
	s_cbranch_vccnz .LBB0_3692
	s_waitcnt vmcnt(13)
	ds_write_b128 v109, v[4:7]
	ds_write_b128 v109, v[8:11] offset:9216
	ds_write_b128 v109, v[16:19] offset:18432
	ds_write_b16 v111, v8 offset:64512
	ds_write_b16_d16_hi v111, v8 offset:64656
	ds_write_b16 v111, v9 offset:64800
	ds_write_b16_d16_hi v111, v9 offset:64944
	ds_write_b16 v111, v10 offset:65088
	ds_write_b16_d16_hi v111, v10 offset:65232
	ds_write_b16 v111, v11 offset:65376
	ds_write_b16_d16_hi v111, v11 offset:65520
	s_and_saveexec_b64 s[8:9], s[38:39]
	v_add_u32_e32 v40, 0, v118
	v_add_u32_e32 v40, 0x18800, v40
	ds_write_b32 v40, v108
	s_or_b64 exec, exec, s[8:9]
	v_mov_b64_e32 v[42:43], v[22:23]
	v_lshlrev_b32_e32 v107, 16, v185
	v_lshlrev_b32_e32 v106, 16, v184
	v_lshlrev_b32_e32 v105, 16, v187
	v_lshlrev_b32_e32 v104, 16, v186
	v_lshlrev_b32_e32 v101, 16, v190
	v_lshlrev_b32_e32 v100, 16, v191
	v_lshlrev_b32_e32 v103, 16, v188
	v_lshlrev_b32_e32 v102, 16, v189
	v_mov_b64_e32 v[40:41], v[20:21]
	s_branch .LBB0_3693
